# grid barrier: generation tracked in a spill lane instead of read back from memory before each arrival
# speedup vs baseline: 1.0134x; 1.0001x over previous
; __device__ __forceinline__ int ltid() { return launder((int)threadIdx.x); }
; __device__ __forceinline__ void prologue(const Params& P) {
;   unsigned char* ws = P.ws; const int tid = ltid();
;   if (blockIdx.x == 0 && tid < 64) {
;     unsigned* ctl = (unsigned*)(ws + WS_CTL);
;     if (tid < 8 || (tid >= 16 && tid < 48)) ctl[tid] = 0u;
; __global__ void __launch_bounds__(512) mega(Params P) {
;   cg::grid_group grid = cg::this_grid();
;   unsigned char* ws = P.ws;
;   if (EN & 1) prologue(P);
_Z4mega6Params:
	s_mov_b32 s96, 0
	v_writelane_b32 v255, s96, 20
	s_load_dwordx16 s[4:19], s[0:1], 0x40
	s_add_u32 s56, s0, 0xa0
	s_load_dword s52, s[0:1], 0xa0
	s_addc_u32 s57, s1, 0
	v_and_b32_e32 v155, 0x3ff, v0
	s_waitcnt lgkmcnt(0)
	v_writelane_b32 v253, s4, 0
	v_mov_b32_e32 v4, v155
	s_cmp_eq_u32 s2, 0
	v_writelane_b32 v253, s5, 1
	v_writelane_b32 v253, s6, 2
	v_writelane_b32 v253, s7, 3
	v_writelane_b32 v253, s8, 4
	v_writelane_b32 v253, s9, 5
	v_writelane_b32 v253, s10, 6
	v_writelane_b32 v253, s11, 7
	v_writelane_b32 v253, s12, 8
	v_writelane_b32 v253, s13, 9
	v_writelane_b32 v253, s14, 10
	v_writelane_b32 v253, s15, 11
	v_writelane_b32 v253, s16, 12
	v_writelane_b32 v253, s17, 13
	v_writelane_b32 v253, s18, 14
	v_writelane_b32 v253, s19, 15
	s_load_dwordx8 s[4:11], s[0:1], 0x80
	s_mov_b32 s37, s2
	s_cselect_b64 s[2:3], -1, 0
	v_cmp_gt_i32_e32 vcc, 64, v4
	s_waitcnt lgkmcnt(0)
	v_writelane_b32 v253, s4, 16
	s_and_b64 s[2:3], s[2:3], vcc
	s_nop 0
	v_writelane_b32 v253, s5, 17
	v_writelane_b32 v253, s6, 18
	v_writelane_b32 v253, s7, 19
	v_writelane_b32 v253, s8, 20
	v_writelane_b32 v253, s9, 21
	v_writelane_b32 v253, s10, 22
	v_writelane_b32 v253, s11, 23
	s_and_saveexec_b64 s[4:5], s[2:3]
	s_cbranch_execz .LBB0_15
	v_add_u32_e32 v1, -16, v4
	v_cmp_lt_i32_e32 vcc, 7, v4
	v_cmp_lt_u32_e64 s[2:3], 31, v1
	s_and_b64 s[2:3], vcc, s[2:3]
	v_mov_b32_e32 v5, 0
	s_and_saveexec_b64 s[6:7], s[2:3]
	s_xor_b64 s[2:3], exec, s[6:7]
	s_or_saveexec_b64 s[2:3], s[2:3]
	v_mov_b64_e32 v[6:7], v[4:5]
	s_xor_b64 exec, exec, s[2:3]
	s_cbranch_execz .LBB0_3
	s_load_dwordx8 s[8:15], s[0:1], 0x80
	v_ashrrev_i32_e32 v7, 31, v4
	v_mov_b32_e32 v6, v4
	v_mov_b32_e32 v1, 0
	s_waitcnt lgkmcnt(0)
	v_lshl_add_u64 v[2:3], v[6:7], 2, s[14:15]
	global_store_dword v[2:3], v1, off

; __global__ void __launch_bounds__(512) mega(Params P) {
;     ...
;     norm_phase(H, P.ffn_norm + l * DM, HN);
;     grid.sync();
.Ln1_done:
.LBB0_225:
	s_or_b64 exec, exec, s[4:5]
	s_barrier
	s_mov_b64 s[2:3], exec
	v_readlane_b32 s0, v253, 57
	v_readlane_b32 s1, v253, 58
	s_and_b64 s[0:1], s[2:3], s[0:1]
	s_mov_b64 exec, s[0:1]
	s_cbranch_execz .LBB0_235
	buffer_wbl2 sc1
	s_load_dwordx2 s[4:5], s[56:57], -0x8
	s_load_dword s0, s[56:57], 0x0
	v_readlane_b32 s1, v253, 55
	s_waitcnt lgkmcnt(0)
	s_and_b32 s1, s1, 7
	s_add_i32 s6, s0, 7
	s_sub_i32 s6, s6, s1
	s_lshr_b32 s6, s6, 3
	s_min_u32 s7, s0, 8
	s_lshl_b32 s1, s1, 2
	s_addk_i32 s1, 0x88
	v_mov_b32_e32 v2, s1
	v_readlane_b32 s96, v255, 20
	s_nop 3
	s_lshl_b32 s97, s96, 16
	v_mov_b32_e32 v0, s97
	s_add_i32 s96, s96, 1
	v_writelane_b32 v255, s96, 20
	v_mov_b32_e32 v3, 1
	s_waitcnt vmcnt(0)
	v_and_b32_e32 v0, 0xffff0000, v0
	global_atomic_add v3, v2, v3, s[4:5] sc0
	s_waitcnt vmcnt(0)
	v_and_b32_e32 v3, 0xffff, v3
	s_nop 0
	v_readfirstlane_b32 s1, v3
	s_nop 3
	s_add_i32 s0, s6, -1
	s_cmp_lg_u32 s1, s0
	s_cbranch_scc1 .Lgb_poll_0
	s_sub_i32 s1, 0x10000, s6
	v_mov_b32_e32 v3, s1
	global_atomic_add v3, v2, v3, s[4:5] sc0
	s_waitcnt vmcnt(0)
	v_mov_b32_e32 v3, 1
	global_atomic_add v3, v1, v3, s[4:5] sc0
	s_waitcnt vmcnt(0)
	v_and_b32_e32 v3, 0xffff, v3
	s_nop 0
	v_readfirstlane_b32 s1, v3
	s_nop 3
	s_add_i32 s0, s7, -1
	s_cmp_lg_u32 s1, s0
	s_cbranch_scc1 .Lgb_poll_0
	s_sub_i32 s1, 0x10000, s7
	v_mov_b32_e32 v3, s1
	global_atomic_add v1, v3, s[4:5]

; __global__ void __launch_bounds__(512) mega(Params P) {
;   cg::grid_group grid = cg::this_grid();
;   unsigned char* ws = P.ws;
;   if (EN & 1) prologue(P);
;   grid.sync();
;   float* H = (float*)(ws + WS_H); bf16_t* HN = (bf16_t*)(ws + WS_HN); bf16_t* CQKV = (bf16_t*)(ws + WS_CQKV);
;   const float2* rope = (const float2*)(ws + WS_ROPE);
;   for (int l = 0; l < 2; ++l) {
;     if (l > 0) { norm_phase(H, P.attn_norm + l * DM, HN); grid.sync(); }
;     { EpiIn e; e.cqkv = CQKV; e.ka = (bf16_t*)(ws + WS_KA); e.qd = (bf16_t*)(ws + WS_QD); e.kd = (bf16_t*)(ws + WS_KD); e.vtd = (bf16_t*)(ws + WS_VTD);
;       e.qs = (bf16_t*)(ws + WS_QS); e.ks = (bf16_t*)(ws + WS_KS); e.vts = (bf16_t*)(ws + WS_VTS); e.rope = rope;
;       if (EN & 2) gemm_phase(HN, DM, (const bf16_t*)(ws + WS_WIN) + (size_t)l * N_IN * 1024, 1024, NREAL, N_IN, 1024, e); }
;     grid.sync();
;     { EpiUp e; e.qa = (bf16_t*)(ws + WS_QA); e.ka = (bf16_t*)(ws + WS_KA); e.vta = (bf16_t*)(ws + WS_VTA); e.rope = rope; e.brow = 0; e.rs_direct = 0.f; e.use_direct = 0;
;       if (EN & 4) up_phase(CQKV, (const bf16_t*)(ws + WS_WQB) + (size_t)l * 768 * 256, (const bf16_t*)(ws + WS_WKVB) + (size_t)l * 768 * 256, e); }
;     grid.sync();
;     attn_phase(P, l);
;     grid.sync();
;     if (l == 0) { EpiResid0 e; e.H = H; e.xsrc = P.x; e.msrc = P.meta; gemm_phase(HN, DM, (const bf16_t*)(ws + WS_WOUT), 1024, NREAL, 1024, 1024, e); }
;     else { EpiResid e; e.H = H; gemm_phase(HN, DM, (const bf16_t*)(ws + WS_WOUT) + (size_t)l * 1024 * 1024, 1024, NREAL, 1024, 1024, e); }
;     grid.sync();
;     norm_phase(H, P.ffn_norm + l * DM, HN);
;     grid.sync();
;     if (EN & 128) { EpiGU e; e.act = (bf16_t*)(ws + WS_ACT); gemm_phase(HN, DM, (const bf16_t*)(ws + WS_WGU) + (size_t)l * N_GU * 1024, 1024, NREAL, N_GU, 1024, e); }
;     grid.sync();
;     if (EN & 256) { EpiResid e; e.H = H; gemm_phase((const bf16_t*)(ws + WS_ACT), DFF, (const bf16_t*)(ws + WS_WDN) + (size_t)l * 1024 * DFF, DFF, NREAL, 1024, DFF, e); }
;     grid.sync();
.LBB0_769:
	s_waitcnt vmcnt(0) lgkmcnt(0)
	s_barrier
	s_mov_b64 s[2:3], exec
	v_readlane_b32 s0, v253, 57
	v_readlane_b32 s1, v253, 58
	s_and_b64 s[0:1], s[2:3], s[0:1]
	s_mov_b64 exec, s[0:1]
	s_cbranch_execz .LBB0_779
	buffer_wbl2 sc1
	s_load_dwordx2 s[4:5], s[56:57], -0x8
	s_load_dword s0, s[56:57], 0x0
	v_readlane_b32 s1, v253, 55
	s_waitcnt lgkmcnt(0)
	s_and_b32 s1, s1, 7
	s_add_i32 s6, s0, 7
	s_sub_i32 s6, s6, s1
	s_lshr_b32 s6, s6, 3
	s_min_u32 s7, s0, 8
	s_lshl_b32 s1, s1, 2
	s_addk_i32 s1, 0x88
	v_mov_b32_e32 v2, s1
	v_readlane_b32 s96, v255, 20
	s_nop 3
	s_lshl_b32 s97, s96, 16
	v_mov_b32_e32 v0, s97
	s_add_i32 s96, s96, 1
	v_writelane_b32 v255, s96, 20
	v_mov_b32_e32 v3, 1
	s_waitcnt vmcnt(0)
	v_and_b32_e32 v0, 0xffff0000, v0
	global_atomic_add v3, v2, v3, s[4:5] sc0
	s_waitcnt vmcnt(0)
	v_and_b32_e32 v3, 0xffff, v3
	s_nop 0
	v_readfirstlane_b32 s1, v3
	s_nop 3
	s_add_i32 s0, s6, -1
	s_cmp_lg_u32 s1, s0
	s_cbranch_scc1 .Lgb_poll_1
	s_sub_i32 s1, 0x10000, s6
	v_mov_b32_e32 v3, s1
	global_atomic_add v3, v2, v3, s[4:5] sc0
	s_waitcnt vmcnt(0)
	v_mov_b32_e32 v3, 1
	global_atomic_add v3, v1, v3, s[4:5] sc0
	s_waitcnt vmcnt(0)
	v_and_b32_e32 v3, 0xffff, v3
	s_nop 0
	v_readfirstlane_b32 s1, v3
	s_nop 3
	s_add_i32 s0, s7, -1
	s_cmp_lg_u32 s1, s0
	s_cbranch_scc1 .Lgb_poll_1
	s_sub_i32 s1, 0x10000, s7
	v_mov_b32_e32 v3, s1
	global_atomic_add v1, v3, s[4:5]

; __global__ void __launch_bounds__(512) mega(Params P) {
;   cg::grid_group grid = cg::this_grid();
;   unsigned char* ws = P.ws;
;   if (EN & 1) prologue(P);
;   grid.sync();
;   float* H = (float*)(ws + WS_H); bf16_t* HN = (bf16_t*)(ws + WS_HN); bf16_t* CQKV = (bf16_t*)(ws + WS_CQKV);
;   const float2* rope = (const float2*)(ws + WS_ROPE);
;   for (int l = 0; l < 2; ++l) {
;     if (l > 0) { norm_phase(H, P.attn_norm + l * DM, HN); grid.sync(); }
;     { EpiIn e; e.cqkv = CQKV; e.ka = (bf16_t*)(ws + WS_KA); e.qd = (bf16_t*)(ws + WS_QD); e.kd = (bf16_t*)(ws + WS_KD); e.vtd = (bf16_t*)(ws + WS_VTD);
;       e.qs = (bf16_t*)(ws + WS_QS); e.ks = (bf16_t*)(ws + WS_KS); e.vts = (bf16_t*)(ws + WS_VTS); e.rope = rope;
;       if (EN & 2) gemm_phase(HN, DM, (const bf16_t*)(ws + WS_WIN) + (size_t)l * N_IN * 1024, 1024, NREAL, N_IN, 1024, e); }
;     grid.sync();
;     { EpiUp e; e.qa = (bf16_t*)(ws + WS_QA); e.ka = (bf16_t*)(ws + WS_KA); e.vta = (bf16_t*)(ws + WS_VTA); e.rope = rope; e.brow = 0; e.rs_direct = 0.f; e.use_direct = 0;
;       if (EN & 4) up_phase(CQKV, (const bf16_t*)(ws + WS_WQB) + (size_t)l * 768 * 256, (const bf16_t*)(ws + WS_WKVB) + (size_t)l * 768 * 256, e); }
;     grid.sync();
;     attn_phase(P, l);
;     grid.sync();
;     if (l == 0) { EpiResid0 e; e.H = H; e.xsrc = P.x; e.msrc = P.meta; gemm_phase(HN, DM, (const bf16_t*)(ws + WS_WOUT), 1024, NREAL, 1024, 1024, e); }
;     else { EpiResid e; e.H = H; gemm_phase(HN, DM, (const bf16_t*)(ws + WS_WOUT) + (size_t)l * 1024 * 1024, 1024, NREAL, 1024, 1024, e); }
;     grid.sync();
;     norm_phase(H, P.ffn_norm + l * DM, HN);
;     grid.sync();
;     if (EN & 128) { EpiGU e; e.act = (bf16_t*)(ws + WS_ACT); gemm_phase(HN, DM, (const bf16_t*)(ws + WS_WGU) + (size_t)l * N_GU * 1024, 1024, NREAL, N_GU, 1024, e); }
;     grid.sync();
;     if (EN & 256) { EpiResid e; e.H = H; gemm_phase((const bf16_t*)(ws + WS_ACT), DFF, (const bf16_t*)(ws + WS_WDN) + (size_t)l * 1024 * DFF, DFF, NREAL, 1024, DFF, e); }
;     grid.sync();
.LBB0_1207:
	s_barrier
	s_mov_b64 s[2:3], exec
	v_readlane_b32 s0, v253, 57
	v_readlane_b32 s1, v253, 58
	s_and_b64 s[0:1], s[2:3], s[0:1]
	s_mov_b64 exec, s[0:1]
	s_cbranch_execz .LBB0_1217
	buffer_wbl2 sc1
	s_load_dwordx2 s[4:5], s[56:57], -0x8
	s_load_dword s0, s[56:57], 0x0
	v_readlane_b32 s1, v253, 55
	s_waitcnt lgkmcnt(0)
	s_and_b32 s1, s1, 7
	s_add_i32 s6, s0, 7
	s_sub_i32 s6, s6, s1
	s_lshr_b32 s6, s6, 3
	s_min_u32 s7, s0, 8
	s_lshl_b32 s1, s1, 2
	s_addk_i32 s1, 0x88
	v_mov_b32_e32 v2, s1
	v_readlane_b32 s96, v255, 20
	s_nop 3
	s_lshl_b32 s97, s96, 16
	v_mov_b32_e32 v0, s97
	s_add_i32 s96, s96, 1
	v_writelane_b32 v255, s96, 20
	v_mov_b32_e32 v3, 1
	s_waitcnt vmcnt(0)
	v_and_b32_e32 v0, 0xffff0000, v0
	global_atomic_add v3, v2, v3, s[4:5] sc0
	s_waitcnt vmcnt(0)
	v_and_b32_e32 v3, 0xffff, v3
	s_nop 0
	v_readfirstlane_b32 s1, v3
	s_nop 3
	s_add_i32 s0, s6, -1
	s_cmp_lg_u32 s1, s0
	s_cbranch_scc1 .Lgb_poll_2
	s_sub_i32 s1, 0x10000, s6
	v_mov_b32_e32 v3, s1
	global_atomic_add v3, v2, v3, s[4:5] sc0
	s_waitcnt vmcnt(0)
	v_mov_b32_e32 v3, 1
	global_atomic_add v3, v1, v3, s[4:5] sc0
	s_waitcnt vmcnt(0)
	v_and_b32_e32 v3, 0xffff, v3
	s_nop 0
	v_readfirstlane_b32 s1, v3
	s_nop 3
	s_add_i32 s0, s7, -1
	s_cmp_lg_u32 s1, s0
	s_cbranch_scc1 .Lgb_poll_2
	s_sub_i32 s1, 0x10000, s7
	v_mov_b32_e32 v3, s1
	global_atomic_add v1, v3, s[4:5]

; __global__ void __launch_bounds__(512) mega(Params P) {
;     ...
;     grid.sync();
.LBB0_1432:
	s_waitcnt lgkmcnt(0)
	s_barrier
	s_mov_b64 s[2:3], exec
	v_readlane_b32 s0, v253, 57
	v_readlane_b32 s1, v253, 58
	v_readlane_b32 s56, v254, 50
	s_and_b64 s[0:1], s[2:3], s[0:1]
	v_readlane_b32 s52, v254, 52
	v_readlane_b32 s57, v254, 51
	v_readlane_b32 s53, v254, 53
	s_mov_b64 exec, s[0:1]
	s_cbranch_execz .LBB0_1442
	buffer_wbl2 sc1
	s_load_dwordx2 s[4:5], s[56:57], -0x8
	s_load_dword s0, s[56:57], 0x0
	v_readlane_b32 s1, v253, 55
	s_waitcnt lgkmcnt(0)
	s_and_b32 s1, s1, 7
	s_add_i32 s6, s0, 7
	s_sub_i32 s6, s6, s1
	s_lshr_b32 s6, s6, 3
	s_min_u32 s7, s0, 8
	s_lshl_b32 s1, s1, 2
	s_addk_i32 s1, 0x88
	v_mov_b32_e32 v2, s1
	v_readlane_b32 s96, v255, 20
	s_nop 3
	s_lshl_b32 s97, s96, 16
	v_mov_b32_e32 v0, s97
	s_add_i32 s96, s96, 1
	v_writelane_b32 v255, s96, 20
	v_mov_b32_e32 v3, 1
	s_waitcnt vmcnt(0)
	v_and_b32_e32 v0, 0xffff0000, v0
	global_atomic_add v3, v2, v3, s[4:5] sc0
	s_waitcnt vmcnt(0)
	v_and_b32_e32 v3, 0xffff, v3
	s_nop 0
	v_readfirstlane_b32 s1, v3
	s_nop 3
	s_add_i32 s0, s6, -1
	s_cmp_lg_u32 s1, s0
	s_cbranch_scc1 .Lgb_poll_3
	s_sub_i32 s1, 0x10000, s6
	v_mov_b32_e32 v3, s1
	global_atomic_add v3, v2, v3, s[4:5] sc0
	s_waitcnt vmcnt(0)
	v_mov_b32_e32 v3, 1
	global_atomic_add v3, v1, v3, s[4:5] sc0
	s_waitcnt vmcnt(0)
	v_and_b32_e32 v3, 0xffff, v3
	s_nop 0
	v_readfirstlane_b32 s1, v3
	s_nop 3
	s_add_i32 s0, s7, -1
	s_cmp_lg_u32 s1, s0
	s_cbranch_scc1 .Lgb_poll_3
	s_sub_i32 s1, 0x10000, s7
	v_mov_b32_e32 v3, s1
	global_atomic_add v1, v3, s[4:5]

; __global__ void __launch_bounds__(512) mega(Params P) {
;     ...
;     grid.sync();
.LBB0_1489:
	s_waitcnt lgkmcnt(0)
	s_barrier
	s_mov_b64 s[4:5], exec
	v_readlane_b32 s0, v253, 57
	v_readlane_b32 s1, v253, 58
	s_and_b64 s[0:1], s[4:5], s[0:1]
	s_mov_b64 exec, s[0:1]
	s_cbranch_execz .LBB0_1499
	buffer_wbl2 sc1
	s_load_dwordx2 s[6:7], s[56:57], -0x8
	s_load_dword s0, s[56:57], 0x0
	v_readlane_b32 s1, v253, 55
	s_waitcnt lgkmcnt(0)
	s_and_b32 s1, s1, 7
	s_add_i32 s8, s0, 7
	s_sub_i32 s8, s8, s1
	s_lshr_b32 s8, s8, 3
	s_min_u32 s9, s0, 8
	s_lshl_b32 s1, s1, 2
	s_addk_i32 s1, 0x88
	v_mov_b32_e32 v2, s1
	v_readlane_b32 s96, v255, 20
	s_nop 3
	s_lshl_b32 s97, s96, 16
	v_mov_b32_e32 v0, s97
	s_add_i32 s96, s96, 1
	v_writelane_b32 v255, s96, 20
	v_mov_b32_e32 v3, 1
	s_waitcnt vmcnt(0)
	v_and_b32_e32 v0, 0xffff0000, v0
	global_atomic_add v3, v2, v3, s[6:7] sc0
	s_waitcnt vmcnt(0)
	v_and_b32_e32 v3, 0xffff, v3
	s_nop 0
	v_readfirstlane_b32 s1, v3
	s_nop 3
	s_add_i32 s0, s8, -1
	s_cmp_lg_u32 s1, s0
	s_cbranch_scc1 .Lgb_poll_4
	s_sub_i32 s1, 0x10000, s8
	v_mov_b32_e32 v3, s1
	global_atomic_add v3, v2, v3, s[6:7] sc0
	s_waitcnt vmcnt(0)
	v_mov_b32_e32 v3, 1
	global_atomic_add v3, v1, v3, s[6:7] sc0
	s_waitcnt vmcnt(0)
	v_and_b32_e32 v3, 0xffff, v3
	s_nop 0
	v_readfirstlane_b32 s1, v3
	s_nop 3
	s_add_i32 s0, s9, -1
	s_cmp_lg_u32 s1, s0
	s_cbranch_scc1 .Lgb_poll_4
	s_sub_i32 s1, 0x10000, s9
	v_mov_b32_e32 v3, s1
	global_atomic_add v1, v3, s[6:7]

; __global__ void __launch_bounds__(512) mega(Params P) {
;     ...
;     grid.sync();
.Ln2_done:
.LBB0_1502:
	s_or_b64 exec, exec, s[6:7]
	s_barrier
	s_mov_b64 s[4:5], exec
	v_readlane_b32 s0, v253, 57
	v_readlane_b32 s1, v253, 58
	s_and_b64 s[0:1], s[4:5], s[0:1]
	s_mov_b64 exec, s[0:1]
	s_cbranch_execz .LBB0_1512
	buffer_wbl2 sc1
	s_load_dwordx2 s[6:7], s[56:57], -0x8
	s_load_dword s0, s[56:57], 0x0
	v_readlane_b32 s1, v253, 55
	s_waitcnt lgkmcnt(0)
	s_and_b32 s1, s1, 7
	s_add_i32 s8, s0, 7
	s_sub_i32 s8, s8, s1
	s_lshr_b32 s8, s8, 3
	s_min_u32 s9, s0, 8
	s_lshl_b32 s1, s1, 2
	s_addk_i32 s1, 0x88
	v_mov_b32_e32 v2, s1
	v_readlane_b32 s96, v255, 20
	s_nop 3
	s_lshl_b32 s97, s96, 16
	v_mov_b32_e32 v0, s97
	s_add_i32 s96, s96, 1
	v_writelane_b32 v255, s96, 20
	v_mov_b32_e32 v3, 1
	s_waitcnt vmcnt(0)
	v_and_b32_e32 v0, 0xffff0000, v0
	global_atomic_add v3, v2, v3, s[6:7] sc0
	s_waitcnt vmcnt(0)
	v_and_b32_e32 v3, 0xffff, v3
	s_nop 0
	v_readfirstlane_b32 s1, v3
	s_nop 3
	s_add_i32 s0, s8, -1
	s_cmp_lg_u32 s1, s0
	s_cbranch_scc1 .Lgb_poll_5
	s_sub_i32 s1, 0x10000, s8
	v_mov_b32_e32 v3, s1
	global_atomic_add v3, v2, v3, s[6:7] sc0
	s_waitcnt vmcnt(0)
	v_mov_b32_e32 v3, 1
	global_atomic_add v3, v1, v3, s[6:7] sc0
	s_waitcnt vmcnt(0)
	v_and_b32_e32 v3, 0xffff, v3
	s_nop 0
	v_readfirstlane_b32 s1, v3
	s_nop 3
	s_add_i32 s0, s9, -1
	s_cmp_lg_u32 s1, s0
	s_cbranch_scc1 .Lgb_poll_5
	s_sub_i32 s1, 0x10000, s9
	v_mov_b32_e32 v3, s1
	global_atomic_add v1, v3, s[6:7]

; __global__ void __launch_bounds__(512) mega(Params P) {
;     ...
;     grid.sync();
.LBB0_1534:
	s_waitcnt vmcnt(0) lgkmcnt(0)
	s_barrier
	s_mov_b64 s[4:5], exec
	v_readlane_b32 s0, v253, 57
	v_readlane_b32 s1, v253, 58
	s_and_b64 s[0:1], s[4:5], s[0:1]
	s_mov_b64 exec, s[0:1]
	s_cbranch_execz .LBB0_1544
	buffer_wbl2 sc1
	s_load_dwordx2 s[6:7], s[56:57], -0x8
	s_load_dword s0, s[56:57], 0x0
	v_readlane_b32 s1, v253, 55
	s_waitcnt lgkmcnt(0)
	s_and_b32 s1, s1, 7
	s_add_i32 s8, s0, 7
	s_sub_i32 s8, s8, s1
	s_lshr_b32 s8, s8, 3
	s_min_u32 s9, s0, 8
	s_lshl_b32 s1, s1, 2
	s_addk_i32 s1, 0x88
	v_mov_b32_e32 v2, s1
	v_readlane_b32 s96, v255, 20
	s_nop 3
	s_lshl_b32 s97, s96, 16
	v_mov_b32_e32 v0, s97
	s_add_i32 s96, s96, 1
	v_writelane_b32 v255, s96, 20
	v_mov_b32_e32 v3, 1
	s_waitcnt vmcnt(0)
	v_and_b32_e32 v0, 0xffff0000, v0
	global_atomic_add v3, v2, v3, s[6:7] sc0
	s_waitcnt vmcnt(0)
	v_and_b32_e32 v3, 0xffff, v3
	s_nop 0
	v_readfirstlane_b32 s1, v3
	s_nop 3
	s_add_i32 s0, s8, -1
	s_cmp_lg_u32 s1, s0
	s_cbranch_scc1 .Lgb_poll_6
	s_sub_i32 s1, 0x10000, s8
	v_mov_b32_e32 v3, s1
	global_atomic_add v3, v2, v3, s[6:7] sc0
	s_waitcnt vmcnt(0)
	v_mov_b32_e32 v3, 1
	global_atomic_add v3, v1, v3, s[6:7] sc0
	s_waitcnt vmcnt(0)
	v_and_b32_e32 v3, 0xffff, v3
	s_nop 0
	v_readfirstlane_b32 s1, v3
	s_nop 3
	s_add_i32 s0, s9, -1
	s_cmp_lg_u32 s1, s0
	s_cbranch_scc1 .Lgb_poll_6
	s_sub_i32 s1, 0x10000, s9
	v_mov_b32_e32 v3, s1
	global_atomic_add v1, v3, s[6:7]

; __global__ void __launch_bounds__(512) mega(Params P) {
;     ...
;     grid.sync();
.LBB0_1567:
	buffer_wbl2 sc1
	s_load_dwordx2 s[4:5], s[56:57], -0x8
	s_load_dword s0, s[56:57], 0x0
	v_readlane_b32 s1, v253, 55
	s_waitcnt lgkmcnt(0)
	s_and_b32 s1, s1, 7
	s_add_i32 s6, s0, 7
	s_sub_i32 s6, s6, s1
	s_lshr_b32 s6, s6, 3
	s_min_u32 s7, s0, 8
	s_lshl_b32 s1, s1, 2
	s_addk_i32 s1, 0x88
	v_mov_b32_e32 v2, s1
	v_readlane_b32 s96, v255, 20
	s_nop 3
	s_lshl_b32 s97, s96, 16
	v_mov_b32_e32 v0, s97
	s_add_i32 s96, s96, 1
	v_writelane_b32 v255, s96, 20
	v_mov_b32_e32 v3, 1
	s_waitcnt vmcnt(0)
	v_and_b32_e32 v0, 0xffff0000, v0
	global_atomic_add v3, v2, v3, s[4:5] sc0
	s_waitcnt vmcnt(0)
	v_and_b32_e32 v3, 0xffff, v3
	s_nop 0
	v_readfirstlane_b32 s1, v3
	s_nop 3
	s_add_i32 s0, s6, -1
	s_cmp_lg_u32 s1, s0
	s_cbranch_scc1 .Lgb_poll_7
	s_sub_i32 s1, 0x10000, s6
	v_mov_b32_e32 v3, s1
	global_atomic_add v3, v2, v3, s[4:5] sc0
	s_waitcnt vmcnt(0)
	v_mov_b32_e32 v3, 1
	global_atomic_add v3, v1, v3, s[4:5] sc0
	s_waitcnt vmcnt(0)
	v_and_b32_e32 v3, 0xffff, v3
	s_nop 0
	v_readfirstlane_b32 s1, v3
	s_nop 3
	s_add_i32 s0, s7, -1
	s_cmp_lg_u32 s1, s0
	s_cbranch_scc1 .Lgb_poll_7
	s_sub_i32 s1, 0x10000, s7
	v_mov_b32_e32 v3, s1
	global_atomic_add v1, v3, s[4:5]
